# stack34 with the per-phase workgroup stagger quartered (s_sleep 0x55 -> 0x15)
# speedup vs baseline: 1.0126x; 1.0008x over previous
.LBB0_149:
	s_add_i32 s6, s6, -1
	s_cmp_eq_u32 s6, 0
	s_sleep 0x15
	s_cbranch_scc0 .LBB0_149

.LBB0_224:
	s_add_i32 s2, s2, -1
	s_cmp_eq_u32 s2, 0
	s_sleep 0x15
	s_cbranch_scc0 .LBB0_224
